# attn2 fast path: zero B-operand dwords hoisted out of the step loop; row-sum chain starts p1+p0 instead of (0+p0)+p1
# speedup vs baseline: 1.0036x; 1.0036x over previous
;     ...
;         f32x16 o[DVB];
; #pragma unroll
;         for (int db = 0; db < DVB; ++db)
; #pragma unroll
;             for (int i = 0; i < 16; ++i) o[db][i] = 0.f;
;         float m = -1e30f, l = 0.f;
;         constexpr bool DEEP = (MODE != 0);
;         u32x4 rgE[NJ], rgO[NJ]; float ckrE = 0.f, ckrO = 0.f;
;     ...
;             u32x4 qxw; qxw.x = hh ? 0u : mb; qxw.y = 0u; qxw.z = 0u; qxw.w = 0u;
.LBB0_3603:
	s_or_b64 exec, exec, s[4:5]
	s_cmp_lt_i32 s40, 1
	s_cbranch_scc1 .LBB0_3591
	v_mad_i64_i32 v[4:5], s[0:1], v1, s29, 0
	v_lshl_add_u64 v[4:5], v[166:167], 0, v[4:5]
	v_mov_b32_e32 v16, v3
	v_mov_b32_e32 v17, v3
	v_lshl_add_u64 v[184:185], v[166:167], 0, v[6:7]
	v_lshl_add_u64 v[186:187], s[22:23], 1, v[4:5]
	v_mov_b32_e32 v2, v3
	v_mov_b32_e32 v4, v3
	v_mov_b32_e32 v5, v3
	v_mov_b32_e32 v6, v3
	v_mov_b32_e32 v7, v3
	v_mov_b32_e32 v8, v3
	v_mov_b32_e32 v9, v3
	v_mov_b32_e32 v10, v3
	v_mov_b32_e32 v11, v3
	v_mov_b32_e32 v12, v3
	v_mov_b32_e32 v13, v3
	v_mov_b32_e32 v14, v3
	v_mov_b32_e32 v15, v3
	v_mov_b64_e32 v[96:97], v[16:17]
	v_mov_b64_e32 v[112:113], v[16:17]
	v_or_b32_e32 v175, 31, v208
	s_mov_b32 s41, 1
	s_mov_b32 s44, 0
	v_mov_b32_e32 v183, 0xf149f2ca
	v_mov_b64_e32 v[190:191], 0
	v_mov_b32_e32 v188, 0
	s_mov_b32 s45, 4
	s_mov_b32 s46, 3
	s_mov_b32 s47, 2
	s_mov_b32 s48, 0
	v_mov_b64_e32 v[94:95], v[14:15]
	v_mov_b64_e32 v[92:93], v[12:13]
	v_mov_b64_e32 v[90:91], v[10:11]
	v_mov_b64_e32 v[88:89], v[8:9]
	v_mov_b64_e32 v[86:87], v[6:7]
	v_mov_b64_e32 v[84:85], v[4:5]
	v_mov_b64_e32 v[82:83], v[2:3]
	v_mov_b64_e32 v[110:111], v[14:15]
	v_mov_b64_e32 v[108:109], v[12:13]
	v_mov_b64_e32 v[106:107], v[10:11]
	v_mov_b64_e32 v[104:105], v[8:9]
	v_mov_b64_e32 v[102:103], v[6:7]
	v_mov_b64_e32 v[100:101], v[4:5]
	v_mov_b64_e32 v[98:99], v[2:3]
	s_mov_b32 s49, 0
	v_mov_b32_e32 v173, 0
	v_mov_b32_e32 v245, v3
	v_mov_b32_e32 v246, v3
	v_mov_b32_e32 v247, v3

; #define MFMA32(a, b, c) __builtin_amdgcn_mfma_f32_32x32x16_bf16((a), (b), (c), 0, 0, 0)
; DI unsigned pk_bf16(float a, float b) { f32x2 v = {a, b}; bf2_t r = __builtin_convertvector(v, bf2_t); return __builtin_bit_cast(unsigned, r); }
;     ...
;             float ls = 0.f;
; #pragma unroll
;             for (int blk = 0; blk < 2; ++blk)
; #pragma unroll
;                 for (int i = 0; i < 16; ++i) { const float e = __builtin_amdgcn_exp2f(s[blk][i]); s[blk][i] = e; ls += e; }
;             l += ls;
;             }
; #pragma unroll
;             for (int blk = 0; blk < 2; ++blk)
; #pragma unroll
;                 for (int sp = 0; sp < 2; ++sp) {
;                     u32x4 pw;
;                     pw.x = pk_bf16(s[blk][8 * sp + 0], s[blk][8 * sp + 1]); pw.y = pk_bf16(s[blk][8 * sp + 2], s[blk][8 * sp + 3]);
;                     pw.z = pk_bf16(s[blk][8 * sp + 4], s[blk][8 * sp + 5]); pw.w = pk_bf16(s[blk][8 * sp + 6], s[blk][8 * sp + 7]);
;                     const bf16x8 pf = __builtin_bit_cast(bf16x8, pw);
; #pragma unroll
;                     for (int db = 0; db < DVB; ++db) {
;                         const unsigned char* va = sb + voff + db * 32 * 136 + (32 * blk + 16 * sp) * 2;
;                         const u32x2 lo = *(const u32x2*)va, hi = *(const u32x2*)(va + 16);
;                         u32x4 vw; vw.x = lo.x; vw.y = lo.y; vw.z = hi.x; vw.w = hi.y;
;                         o[db] = MFMA32(__builtin_bit_cast(bf16x8, vw), pf, o[db]);
;                     }
;                 }
.LBB0_3617:
	s_mul_hi_u32 s0, s49, 0xaaaaaaab
	s_lshr_b32 s0, s0, 1
	s_mul_i32 s0, s0, 0xd800
	v_exp_f32_e32 v35, v1
	v_subrev_u32_e32 v1, s0, v196
	v_add3_u32 v1, v199, s48, v1
	v_exp_f32_e32 v34, v2
	v_add_u32_e32 v2, 0x2000, v1
	ds_read2_b64 v[44:47], v2 offset0:128 offset1:130
	v_exp_f32_e32 v18, v18
	v_exp_f32_e32 v19, v19
	v_exp_f32_e32 v20, v20
	v_exp_f32_e32 v21, v21
	v_exp_f32_e32 v22, v22
	v_exp_f32_e32 v23, v23
	v_exp_f32_e32 v24, v24
	v_exp_f32_e32 v25, v25
	v_cvt_pk_bf16_f32 v40, v18, v19
	v_cvt_pk_bf16_f32 v41, v20, v21
	v_cvt_pk_bf16_f32 v42, v22, v23
	v_cvt_pk_bf16_f32 v43, v24, v25
	v_add_u32_e32 v1, 0x3000, v1
	v_exp_f32_e32 v36, v4
	s_waitcnt lgkmcnt(0)
	v_mfma_f32_32x32x16_bf16 v[98:113], v[44:47], v[40:43], v[98:113]
	ds_read2_b64 v[44:47], v1 offset0:160 offset1:162
	v_add_f32_e32 v4, v19, v18
	v_add_f32_e32 v4, v20, v4
	v_add_f32_e32 v4, v21, v4
	v_exp_f32_e32 v26, v26
	v_add_f32_e32 v4, v22, v4
	v_exp_f32_e32 v27, v27
	v_add_f32_e32 v4, v23, v4
	v_exp_f32_e32 v28, v28
	v_add_f32_e32 v4, v24, v4
	v_exp_f32_e32 v29, v29
	v_add_f32_e32 v4, v25, v4
	v_exp_f32_e32 v30, v30
	v_add_f32_e32 v4, v26, v4
	v_exp_f32_e32 v31, v31
	s_waitcnt lgkmcnt(0)
	v_mfma_f32_32x32x16_bf16 v[82:97], v[44:47], v[40:43], v[82:97]
	v_add_f32_e32 v4, v27, v4
	ds_read2_b64 v[40:43], v2 offset0:132 offset1:134
	v_exp_f32_e32 v32, v32
	v_add_f32_e32 v4, v28, v4
	v_exp_f32_e32 v33, v33
	v_add_f32_e32 v4, v29, v4
	v_add_f32_e32 v4, v30, v4
	v_add_f32_e32 v4, v31, v4
	v_add_f32_e32 v4, v32, v4
	v_exp_f32_e32 v37, v17
	v_add_f32_e32 v4, v33, v4
	v_exp_f32_e32 v38, v16
	v_add_f32_e32 v4, v34, v4
	v_add_f32_e32 v4, v35, v4
	v_exp_f32_e32 v39, v5
	v_cvt_pk_bf16_f32 v44, v26, v27
	v_cvt_pk_bf16_f32 v45, v28, v29
	v_cvt_pk_bf16_f32 v46, v30, v31
	v_cvt_pk_bf16_f32 v47, v32, v33
	ds_read2_b64 v[114:117], v1 offset0:164 offset1:166
	v_add_f32_e32 v4, v36, v4
	s_waitcnt lgkmcnt(1)
	v_mfma_f32_32x32x16_bf16 v[98:113], v[40:43], v[44:47], v[98:113]
	v_exp_f32_e32 v40, v6
	v_add_f32_e32 v4, v37, v4
	v_exp_f32_e32 v41, v7
	v_add_f32_e32 v4, v38, v4
	v_add_f32_e32 v4, v39, v4
	v_add_f32_e32 v4, v40, v4
	v_add_f32_e32 v16, v41, v4
	ds_read2_b64 v[4:7], v2 offset0:136 offset1:138
	ds_read2_b64 v[118:121], v1 offset0:168 offset1:170
	s_waitcnt lgkmcnt(2)
	v_mfma_f32_32x32x16_bf16 v[82:97], v[114:117], v[44:47], v[82:97]
	v_exp_f32_e32 v42, v8
	v_exp_f32_e32 v43, v9
	v_cvt_pk_bf16_f32 v114, v34, v35
	v_cvt_pk_bf16_f32 v115, v36, v37
	v_cvt_pk_bf16_f32 v116, v38, v39
	v_cvt_pk_bf16_f32 v117, v40, v41
	v_exp_f32_e32 v46, v12
	v_exp_f32_e32 v47, v13
	s_waitcnt lgkmcnt(1)
	v_mfma_f32_32x32x16_bf16 v[98:113], v[4:7], v[114:117], v[98:113]
	v_add_f32_e32 v4, v42, v16
	v_add_f32_e32 v16, v43, v4
	ds_read2_b64 v[4:7], v2 offset0:140 offset1:142
	v_exp_f32_e32 v48, v14
	v_exp_f32_e32 v49, v15
	ds_read2_b64 v[12:15], v1 offset0:172 offset1:174
	v_exp_f32_e32 v44, v10
	s_waitcnt lgkmcnt(2)
	v_mfma_f32_32x32x16_bf16 v[82:97], v[118:121], v[114:117], v[82:97]
	v_exp_f32_e32 v45, v11
	v_cvt_pk_bf16_f32 v8, v42, v43
	v_cvt_pk_bf16_f32 v10, v46, v47
	v_cvt_pk_bf16_f32 v11, v48, v49
	v_cvt_pk_bf16_f32 v9, v44, v45
	v_add_f32_e32 v1, v44, v16
	v_add_f32_e32 v1, v45, v1
	s_waitcnt lgkmcnt(1)
	v_mfma_f32_32x32x16_bf16 v[98:113], v[4:7], v[8:11], v[98:113]
	v_add_f32_e32 v1, v46, v1
	v_add_f32_e32 v1, v47, v1
	v_add_f32_e32 v1, v48, v1
	v_add_f32_e32 v1, v49, v1
	v_add_f32_e32 v173, v173, v1
	s_waitcnt lgkmcnt(0)
	v_mfma_f32_32x32x16_bf16 v[82:97], v[12:15], v[8:11], v[82:97]

; #define MFMA32(a, b, c) __builtin_amdgcn_mfma_f32_32x32x16_bf16((a), (b), (c), 0, 0, 0)
; DI unsigned pk_bf16(float a, float b) { f32x2 v = {a, b}; bf2_t r = __builtin_convertvector(v, bf2_t); return __builtin_bit_cast(unsigned, r); }
;     ...
;             float ls = 0.f;
; #pragma unroll
;             for (int blk = 0; blk < 2; ++blk)
; #pragma unroll
;                 for (int i = 0; i < 16; ++i) { const float e = __builtin_amdgcn_exp2f(s[blk][i]); s[blk][i] = e; ls += e; }
;             l += ls;
;             }
; #pragma unroll
;             for (int blk = 0; blk < 2; ++blk)
; #pragma unroll
;                 for (int sp = 0; sp < 2; ++sp) {
;                     u32x4 pw;
;                     pw.x = pk_bf16(s[blk][8 * sp + 0], s[blk][8 * sp + 1]); pw.y = pk_bf16(s[blk][8 * sp + 2], s[blk][8 * sp + 3]);
;                     pw.z = pk_bf16(s[blk][8 * sp + 4], s[blk][8 * sp + 5]); pw.w = pk_bf16(s[blk][8 * sp + 6], s[blk][8 * sp + 7]);
;                     const bf16x8 pf = __builtin_bit_cast(bf16x8, pw);
; #pragma unroll
;                     for (int db = 0; db < DVB; ++db) {
;                         const unsigned char* va = sb + voff + db * 32 * 136 + (32 * blk + 16 * sp) * 2;
;                         const u32x2 lo = *(const u32x2*)va, hi = *(const u32x2*)(va + 16);
;                         u32x4 vw; vw.x = lo.x; vw.y = lo.y; vw.z = hi.x; vw.w = hi.y;
;                         o[db] = MFMA32(__builtin_bit_cast(bf16x8, vw), pf, o[db]);
;                     }
;                 }
.LBB0_3635:
	v_exp_f32_e32 v51, v1
	v_subrev_u32_e32 v1, s51, v196
	v_add3_u32 v1, v199, s48, v1
	v_exp_f32_e32 v50, v2
	v_add_u32_e32 v2, 0x6800, v1
	ds_read2_b64 v[76:79], v2 offset0:128 offset1:130
	v_exp_f32_e32 v52, v4
	v_exp_f32_e32 v53, v17
	v_exp_f32_e32 v54, v16
	v_exp_f32_e32 v55, v55
	v_exp_f32_e32 v56, v56
	v_exp_f32_e32 v57, v57
	v_cvt_pk_bf16_f32 v72, v50, v51
	v_cvt_pk_bf16_f32 v73, v52, v53
	v_cvt_pk_bf16_f32 v74, v54, v55
	v_cvt_pk_bf16_f32 v75, v56, v57
	v_add_u32_e32 v1, 0x7800, v1
	s_waitcnt lgkmcnt(0)
	v_mfma_f32_32x32x16_bf16 v[98:113], v[76:79], v[72:75], v[98:113]
	ds_read2_b64 v[76:79], v1 offset0:160 offset1:162
	v_add_f32_e32 v4, v51, v50
	v_add_f32_e32 v4, v52, v4
	v_add_f32_e32 v4, v53, v4
	v_exp_f32_e32 v58, v58
	v_add_f32_e32 v4, v54, v4
	v_exp_f32_e32 v59, v59
	v_add_f32_e32 v4, v55, v4
	v_exp_f32_e32 v60, v60
	v_add_f32_e32 v4, v56, v4
	v_exp_f32_e32 v61, v61
	v_add_f32_e32 v4, v57, v4
	v_exp_f32_e32 v62, v62
	v_add_f32_e32 v4, v58, v4
	v_exp_f32_e32 v63, v63
	s_waitcnt lgkmcnt(0)
	v_mfma_f32_32x32x16_bf16 v[82:97], v[76:79], v[72:75], v[82:97]
	v_add_f32_e32 v4, v59, v4
	ds_read2_b64 v[72:75], v2 offset0:132 offset1:134
	v_exp_f32_e32 v64, v64
	v_add_f32_e32 v4, v60, v4
	v_exp_f32_e32 v65, v65
	v_add_f32_e32 v4, v61, v4
	v_exp_f32_e32 v66, v66
	v_add_f32_e32 v4, v62, v4
	v_exp_f32_e32 v67, v67
	v_add_f32_e32 v4, v63, v4
	v_exp_f32_e32 v68, v68
	v_add_f32_e32 v4, v64, v4
	v_exp_f32_e32 v69, v69
	v_add_f32_e32 v4, v65, v4
	v_exp_f32_e32 v70, v70
	v_add_f32_e32 v4, v66, v4
	v_add_f32_e32 v4, v67, v4
	v_exp_f32_e32 v71, v5
	v_cvt_pk_bf16_f32 v76, v58, v59
	v_cvt_pk_bf16_f32 v77, v60, v61
	v_cvt_pk_bf16_f32 v78, v62, v63
	v_cvt_pk_bf16_f32 v79, v64, v65
	ds_read2_b64 v[116:119], v1 offset0:164 offset1:166
	v_add_f32_e32 v4, v68, v4
	s_waitcnt lgkmcnt(1)
	v_mfma_f32_32x32x16_bf16 v[98:113], v[72:75], v[76:79], v[98:113]
	v_exp_f32_e32 v72, v6
	v_add_f32_e32 v4, v69, v4
	v_exp_f32_e32 v73, v7
	v_add_f32_e32 v4, v70, v4
	v_add_f32_e32 v4, v71, v4
	v_add_f32_e32 v4, v72, v4
	v_add_f32_e32 v16, v73, v4
	ds_read2_b64 v[4:7], v2 offset0:136 offset1:138
	ds_read2_b64 v[120:123], v1 offset0:168 offset1:170
	s_waitcnt lgkmcnt(2)
	v_mfma_f32_32x32x16_bf16 v[82:97], v[116:119], v[76:79], v[82:97]
	v_exp_f32_e32 v74, v8
	v_exp_f32_e32 v75, v9
	v_cvt_pk_bf16_f32 v116, v66, v67
	v_cvt_pk_bf16_f32 v117, v68, v69
	v_cvt_pk_bf16_f32 v118, v70, v71
	v_cvt_pk_bf16_f32 v119, v72, v73
	v_exp_f32_e32 v78, v12
	v_exp_f32_e32 v79, v13
	s_waitcnt lgkmcnt(1)
	v_mfma_f32_32x32x16_bf16 v[98:113], v[4:7], v[116:119], v[98:113]
	v_add_f32_e32 v4, v74, v16
	v_add_f32_e32 v16, v75, v4
	ds_read2_b64 v[4:7], v2 offset0:140 offset1:142
	v_exp_f32_e32 v80, v14
	v_exp_f32_e32 v81, v15
	ds_read2_b64 v[12:15], v1 offset0:172 offset1:174
	v_exp_f32_e32 v76, v10
	s_waitcnt lgkmcnt(2)
	v_mfma_f32_32x32x16_bf16 v[82:97], v[120:123], v[116:119], v[82:97]
	v_exp_f32_e32 v77, v11
	v_cvt_pk_bf16_f32 v8, v74, v75
	v_cvt_pk_bf16_f32 v10, v78, v79
	v_cvt_pk_bf16_f32 v11, v80, v81
	v_cvt_pk_bf16_f32 v9, v76, v77
	v_add_f32_e32 v1, v76, v16
	v_add_f32_e32 v1, v77, v1
	s_waitcnt lgkmcnt(1)
	v_mfma_f32_32x32x16_bf16 v[98:113], v[4:7], v[8:11], v[98:113]
	v_add_f32_e32 v1, v78, v1
	v_add_f32_e32 v1, v79, v1
	v_add_f32_e32 v1, v80, v1
	v_add_f32_e32 v1, v81, v1
	v_add_f32_e32 v173, v173, v1
	s_waitcnt lgkmcnt(0)
	v_mfma_f32_32x32x16_bf16 v[82:97], v[12:15], v[8:11], v[82:97]

;     ...
;         auto qk = [&](f32x16 (&s)[2], float& mi, int stg) {
;             const unsigned char* kb_ = lds + stg * STG + koff;
;             const unsigned mb = pk_bf16((m > -1e29f) ? -m : 0.f, 0.f) & 0xffffu;
;             mi = -__uint_as_float(mb << 16);
;             u32x4 qxw; qxw.x = hh ? 0u : mb; qxw.y = 0u; qxw.z = 0u; qxw.w = 0u;
;             u32x4 kxw; kxw.x = hh ? 0u : 0x3f80u; kxw.y = 0u; kxw.z = 0u; kxw.w = 0u;
;             const bf16x8 qx = __builtin_bit_cast(bf16x8, qxw), kx = __builtin_bit_cast(bf16x8, kxw);
;             f32x16 zero;
; #pragma unroll
;             for (int i = 0; i < 16; ++i) zero[i] = 0.f;
; #pragma unroll
;             for (int blk = 0; blk < 2; ++blk) {
;                 s[blk] = MFMA32(kx, qx, zero);
; #pragma unroll
;                 for (int ks = 0; ks < 4; ++ks) {
;                     const bf16x8 kf = *(const bf16x8*)(kb_ + blk * 4608 + ks * 32);
;                     s[blk] = MFMA32(kf, qf[ks], s[blk]);
;                 }
;             }
;     ...
;             if (MODE == 2) {
;                 const u64 wsh = wcur >> (4 * hh);
;                 const int wlo = (int)(unsigned)wsh, whi = (int)(unsigned)(wsh >> 32);
; #pragma unroll
;                 for (int i = 0; i < 16; ++i) {
;                     const int bit = (i & 3) + 8 * (i >> 2);
;                     const unsigned m0 = (unsigned)__builtin_amdgcn_sbfe(wlo, bit, 1), m1 = (unsigned)__builtin_amdgcn_sbfe(whi, bit, 1);
;                     s[0][i] = __uint_as_float((__float_as_uint(s[0][i]) & m0) | (0xff800000u & ~m0));
;                     s[1][i] = __uint_as_float((__float_as_uint(s[1][i]) & m1) | (0xff800000u & ~m1));
;                 }
;             } else if (k0 + 63 > qw0) {
; #pragma unroll
;                 for (int blk = 0; blk < 2; ++blk)
; #pragma unroll
;                     for (int i = 0; i < 16; ++i) { const int key = k0 + 32 * blk + crow(i, hh); if (key > myq) s[blk][i] = -INFINITY; }
;             }
;             float mx = s[0][0];
; #pragma unroll
;             for (int i = 1; i < 16; ++i) mx = fmaxf(mx, s[0][i]);
; #pragma unroll
;             for (int i = 0; i < 16; ++i) mx = fmaxf(mx, s[1][i]);
;             mx = xhalf_max(mx);
;             const float mabs = mi + mx;
;             const bool up = mabs > m + 8.0f;
;             const float mn = up ? __uint_as_float(pk_bf16(mabs, 0.f) << 16) : m;
;             const float shift = mn - mi;
.Lil1_fast:
	s_mov_b64 s[26:27], exec
	v_cmp_lt_f32_e64 s[4:5], s31, v183
	s_mov_b64 vcc, s[2:3]
	s_nop 0
	v_cndmask_b32_e64 v244, 0, -v183, s[4:5]
	v_cvt_pk_bf16_f32 v248, v244, 0
	v_cndmask_b32_sdwa v244, v3, v248, vcc dst_sel:DWORD dst_unused:UNUSED_PAD src0_sel:DWORD src1_sel:WORD_0
	v_lshlrev_b32_e32 v249, 16, v248
	v_xor_b32_e32 v188, 0x80000000, v249
	v_mfma_f32_32x32x16_bf16 v[66:81], v[130:133], v[244:247], 0
	v_lshrrev_b64 v[6:7], v170, v[116:117]
	v_bfe_i32 v1, v6, 0, 1
	v_bitop3_b32 v18, v18, s34, v1 bitop3:0xe4
	v_bfe_i32 v1, v6, 1, 1
	v_bfe_i32 v4, v7, 1, 1
	v_bfe_i32 v2, v7, 0, 1
	v_bitop3_b32 v19, v19, s34, v1 bitop3:0xe4
	v_bitop3_b32 v1, v35, s34, v4 bitop3:0xe4
	v_bfe_i32 v4, v6, 2, 1
	v_bfe_i32 v5, v7, 2, 1
	v_bitop3_b32 v2, v34, s34, v2 bitop3:0xe4
	s_waitcnt lgkmcnt(7)
	v_mfma_f32_32x32x16_bf16 v[50:65], v[212:215], v[142:145], v[66:81]
	v_bitop3_b32 v20, v20, s34, v4 bitop3:0xe4
	v_bitop3_b32 v4, v36, s34, v5 bitop3:0xe4
	v_bfe_i32 v5, v6, 3, 1
	v_bfe_i32 v8, v7, 3, 1
	v_bfe_i32 v10, v6, 11, 1
	v_bfe_i32 v34, v6, 18, 1
	v_bfe_i32 v35, v7, 18, 1
	v_bitop3_b32 v21, v21, s34, v5 bitop3:0xe4
	v_bitop3_b32 v17, v37, s34, v8 bitop3:0xe4
	v_bfe_i32 v5, v6, 8, 1
	s_waitcnt lgkmcnt(6)
	v_mfma_f32_32x32x16_bf16 v[50:65], v[216:219], v[146:149], v[50:65]
	v_bfe_i32 v8, v7, 8, 1
	v_bitop3_b32 v25, v25, s34, v10 bitop3:0xe4
	v_bitop3_b32 v28, v28, s34, v34 bitop3:0xe4
	v_bitop3_b32 v10, v44, s34, v35 bitop3:0xe4
	v_bitop3_b32 v22, v22, s34, v5 bitop3:0xe4
	v_bitop3_b32 v16, v38, s34, v8 bitop3:0xe4
	v_bfe_i32 v5, v6, 9, 1
	v_bfe_i32 v8, v7, 9, 1
	v_max_f32_e32 v34, v18, v19
	s_waitcnt lgkmcnt(5)
	v_mfma_f32_32x32x16_bf16 v[50:65], v[220:223], v[150:153], v[50:65]
	v_bitop3_b32 v23, v23, s34, v5 bitop3:0xe4
	v_bitop3_b32 v5, v39, s34, v8 bitop3:0xe4
	v_bfe_i32 v8, v6, 10, 1
	v_max3_f32 v34, v34, v20, v21
	v_bfe_i32 v12, v6, 16, 1
	v_bfe_i32 v14, v6, 17, 1
	v_bitop3_b32 v24, v24, s34, v8 bitop3:0xe4
	v_max3_f32 v34, v34, v22, v23
	v_bfe_i32 v36, v6, 19, 1
	v_bitop3_b32 v26, v26, s34, v12 bitop3:0xe4
	v_bitop3_b32 v27, v27, s34, v14 bitop3:0xe4
	s_waitcnt lgkmcnt(4)
	v_mfma_f32_32x32x16_bf16 v[50:65], v[224:227], v[154:157], v[50:65]
	v_max3_f32 v34, v34, v24, v25
	v_bfe_i32 v38, v6, 24, 1
	v_bfe_i32 v114, v6, 25, 1
	v_bitop3_b32 v29, v29, s34, v36 bitop3:0xe4
	v_max3_f32 v34, v34, v26, v27
	v_bfe_i32 v116, v6, 26, 1
	v_bfe_i32 v118, v6, 27, 1
	v_bitop3_b32 v30, v30, s34, v38 bitop3:0xe4
	v_bitop3_b32 v31, v31, s34, v114 bitop3:0xe4
	v_max3_f32 v34, v34, v28, v29
	s_waitcnt lgkmcnt(3)
	v_mfma_f32_32x32x16_bf16 v[66:81], v[228:231], v[142:145], v[66:81]
	v_bitop3_b32 v32, v32, s34, v116 bitop3:0xe4
	v_bitop3_b32 v33, v33, s34, v118 bitop3:0xe4
	v_max3_f32 v34, v34, v30, v31
	v_max3_f32 v34, v34, v32, v33
	v_max3_f32 v34, v34, v2, v1
	v_bfe_i32 v9, v7, 10, 1
	v_bfe_i32 v11, v7, 11, 1
	v_max3_f32 v34, v34, v4, v17
	v_bfe_i32 v13, v7, 16, 1
	v_bfe_i32 v15, v7, 17, 1
	v_bfe_i32 v37, v7, 19, 1
	s_waitcnt lgkmcnt(2)
	v_mfma_f32_32x32x16_bf16 v[66:81], v[232:235], v[146:149], v[66:81]
	v_bfe_i32 v39, v7, 24, 1
	v_bfe_i32 v115, v7, 25, 1
	v_bfe_i32 v117, v7, 26, 1
	v_bfe_i32 v119, v7, 27, 1
	v_bitop3_b32 v6, v40, s34, v9 bitop3:0xe4
	v_bitop3_b32 v7, v41, s34, v11 bitop3:0xe4
	v_max3_f32 v34, v34, v16, v5
	v_bitop3_b32 v8, v42, s34, v13 bitop3:0xe4
	v_bitop3_b32 v9, v43, s34, v15 bitop3:0xe4
	v_max3_f32 v34, v34, v6, v7
	v_bitop3_b32 v11, v45, s34, v37 bitop3:0xe4
	s_waitcnt lgkmcnt(1)
	v_mfma_f32_32x32x16_bf16 v[66:81], v[236:239], v[150:153], v[66:81]
	v_max3_f32 v34, v34, v8, v9
	v_bitop3_b32 v12, v46, s34, v39 bitop3:0xe4
	v_bitop3_b32 v13, v47, s34, v115 bitop3:0xe4
	v_max3_f32 v34, v34, v10, v11
	v_bitop3_b32 v14, v48, s34, v117 bitop3:0xe4
	v_bitop3_b32 v15, v49, s34, v119 bitop3:0xe4
	v_max3_f32 v34, v34, v12, v13
	v_max3_f32 v34, v34, v14, v15
	v_mov_b32_e32 v35, v34
	s_nop 1
	s_waitcnt lgkmcnt(0)
	v_mfma_f32_32x32x16_bf16 v[66:81], v[240:243], v[154:157], v[66:81]
	v_permlane32_swap_b32_e32 v34, v35
	v_max_f32_e32 v176, v34, v35
	v_pk_add_f32 v[34:35], v[182:183], v[176:177]
	s_nop 0
	v_cvt_pk_bf16_f32 v36, v34, 0
	v_lshlrev_b32_e32 v36, 16, v36
	v_cmp_gt_f32_e64 s[4:5], v34, v35
	s_nop 1
	v_cndmask_b32_e64 v189, v183, v36, s[4:5]
	v_sub_f32_e32 v176, v189, v182
	v_cmp_neq_f32_e32 vcc, 0, v176
	s_cbranch_vccz .LBB0_3617
	s_branch .Lil1_cont
;     ...
;         auto qk = [&](f32x16 (&s)[2], float& mi, int stg) {
;             const unsigned char* kb_ = lds + stg * STG + koff;
;             const unsigned mb = pk_bf16((m > -1e29f) ? -m : 0.f, 0.f) & 0xffffu;
;             mi = -__uint_as_float(mb << 16);
;             u32x4 qxw; qxw.x = hh ? 0u : mb; qxw.y = 0u; qxw.z = 0u; qxw.w = 0u;
;             u32x4 kxw; kxw.x = hh ? 0u : 0x3f80u; kxw.y = 0u; kxw.z = 0u; kxw.w = 0u;
;             const bf16x8 qx = __builtin_bit_cast(bf16x8, qxw), kx = __builtin_bit_cast(bf16x8, kxw);
;             f32x16 zero;
; #pragma unroll
;             for (int i = 0; i < 16; ++i) zero[i] = 0.f;
; #pragma unroll
;             for (int blk = 0; blk < 2; ++blk) {
;                 s[blk] = MFMA32(kx, qx, zero);
; #pragma unroll
;                 for (int ks = 0; ks < 4; ++ks) {
;                     const bf16x8 kf = *(const bf16x8*)(kb_ + blk * 4608 + ks * 32);
;                     s[blk] = MFMA32(kf, qf[ks], s[blk]);
;                 }
;             }
;     ...
;             if (MODE == 2) {
;                 const u64 wsh = wcur >> (4 * hh);
;                 const int wlo = (int)(unsigned)wsh, whi = (int)(unsigned)(wsh >> 32);
; #pragma unroll
;                 for (int i = 0; i < 16; ++i) {
;                     const int bit = (i & 3) + 8 * (i >> 2);
;                     const unsigned m0 = (unsigned)__builtin_amdgcn_sbfe(wlo, bit, 1), m1 = (unsigned)__builtin_amdgcn_sbfe(whi, bit, 1);
;                     s[0][i] = __uint_as_float((__float_as_uint(s[0][i]) & m0) | (0xff800000u & ~m0));
;                     s[1][i] = __uint_as_float((__float_as_uint(s[1][i]) & m1) | (0xff800000u & ~m1));
;                 }
;             } else if (k0 + 63 > qw0) {
; #pragma unroll
;                 for (int blk = 0; blk < 2; ++blk)
; #pragma unroll
;                     for (int i = 0; i < 16; ++i) { const int key = k0 + 32 * blk + crow(i, hh); if (key > myq) s[blk][i] = -INFINITY; }
;             }
;             float mx = s[0][0];
; #pragma unroll
;             for (int i = 1; i < 16; ++i) mx = fmaxf(mx, s[0][i]);
; #pragma unroll
;             for (int i = 0; i < 16; ++i) mx = fmaxf(mx, s[1][i]);
;             mx = xhalf_max(mx);
;             const float mabs = mi + mx;
;             const bool up = mabs > m + 8.0f;
;             const float mn = up ? __uint_as_float(pk_bf16(mabs, 0.f) << 16) : m;
;             const float shift = mn - mi;
.Lil2_fast:
	s_mov_b64 s[24:25], exec
	s_add_i32 s0, s44, 64
	v_cmp_lt_f32_e64 s[6:7], s31, v183
	s_mov_b64 vcc, s[2:3]
	s_nop 0
	v_cndmask_b32_e64 v244, 0, -v183, s[6:7]
	v_cvt_pk_bf16_f32 v248, v244, 0
	v_cndmask_b32_sdwa v244, v3, v248, vcc dst_sel:DWORD dst_unused:UNUSED_PAD src0_sel:DWORD src1_sel:WORD_0
	v_lshlrev_b32_e32 v249, 16, v248
	v_xor_b32_e32 v182, 0x80000000, v249
	v_mfma_f32_32x32x16_bf16 v[34:49], v[130:133], v[244:247], 0
	v_lshrrev_b64 v[6:7], v170, v[192:193]
	v_bfe_i32 v10, v6, 3, 1
	v_bfe_i32 v1, v6, 0, 1
	v_bitop3_b32 v17, v53, s34, v10 bitop3:0xe4
	v_bfe_i32 v10, v6, 8, 1
	v_bitop3_b32 v2, v50, s34, v1 bitop3:0xe4
	v_bfe_i32 v1, v6, 1, 1
	v_bitop3_b32 v16, v54, s34, v10 bitop3:0xe4
	v_bfe_i32 v10, v6, 9, 1
	v_bfe_i32 v8, v7, 1, 1
	v_bitop3_b32 v1, v51, s34, v1 bitop3:0xe4
	s_waitcnt lgkmcnt(7)
	v_mfma_f32_32x32x16_bf16 v[18:33], v[212:215], v[142:145], v[34:49]
	v_bfe_i32 v9, v7, 2, 1
	v_bitop3_b32 v55, v55, s34, v10 bitop3:0xe4
	v_bfe_i32 v10, v6, 10, 1
	v_bfe_i32 v50, v7, 16, 1
	v_bfe_i32 v51, v7, 17, 1
	v_bfe_i32 v4, v6, 2, 1
	v_bitop3_b32 v56, v56, s34, v10 bitop3:0xe4
	v_bfe_i32 v10, v6, 11, 1
	v_bitop3_b32 v67, v67, s34, v8 bitop3:0xe4
	v_bitop3_b32 v68, v68, s34, v9 bitop3:0xe4
	v_bitop3_b32 v8, v74, s34, v50 bitop3:0xe4
	s_waitcnt lgkmcnt(6)
	v_mfma_f32_32x32x16_bf16 v[18:33], v[216:219], v[146:149], v[18:33]
	v_bitop3_b32 v9, v75, s34, v51 bitop3:0xe4
	v_bitop3_b32 v4, v52, s34, v4 bitop3:0xe4
	v_bitop3_b32 v57, v57, s34, v10 bitop3:0xe4
	v_bfe_i32 v10, v6, 16, 1
	v_max_f32_e32 v50, v2, v1
	v_bitop3_b32 v58, v58, s34, v10 bitop3:0xe4
	v_bfe_i32 v10, v6, 17, 1
	v_max3_f32 v50, v50, v4, v17
	s_waitcnt lgkmcnt(5)
	v_mfma_f32_32x32x16_bf16 v[18:33], v[220:223], v[150:153], v[18:33]
	v_bitop3_b32 v59, v59, s34, v10 bitop3:0xe4
	v_bfe_i32 v10, v6, 18, 1
	v_max3_f32 v50, v50, v16, v55
	v_bitop3_b32 v60, v60, s34, v10 bitop3:0xe4
	v_bfe_i32 v10, v6, 19, 1
	v_max3_f32 v50, v50, v56, v57
	v_bfe_i32 v54, v6, 24, 1
	v_bfe_i32 v117, v6, 25, 1
	v_bitop3_b32 v61, v61, s34, v10 bitop3:0xe4
	v_max3_f32 v50, v50, v58, v59
	v_bfe_i32 v119, v6, 26, 1
	s_waitcnt lgkmcnt(4)
	v_mfma_f32_32x32x16_bf16 v[18:33], v[224:227], v[154:157], v[18:33]
	v_bfe_i32 v6, v6, 27, 1
	v_bitop3_b32 v62, v62, s34, v54 bitop3:0xe4
	v_bitop3_b32 v63, v63, s34, v117 bitop3:0xe4
	v_max3_f32 v50, v50, v60, v61
	v_bfe_i32 v5, v7, 0, 1
	v_bitop3_b32 v64, v64, s34, v119 bitop3:0xe4
	v_bitop3_b32 v65, v65, s34, v6 bitop3:0xe4
	v_max3_f32 v50, v50, v62, v63
	v_bfe_i32 v11, v7, 3, 1
	v_bitop3_b32 v66, v66, s34, v5 bitop3:0xe4
	v_max3_f32 v50, v50, v64, v65
	s_waitcnt lgkmcnt(3)
	v_mfma_f32_32x32x16_bf16 v[34:49], v[228:231], v[142:145], v[34:49]
	v_bfe_i32 v12, v7, 8, 1
	v_bfe_i32 v13, v7, 9, 1
	v_bitop3_b32 v69, v69, s34, v11 bitop3:0xe4
	v_max3_f32 v50, v50, v66, v67
	v_bfe_i32 v14, v7, 10, 1
	v_bfe_i32 v15, v7, 11, 1
	v_bitop3_b32 v70, v70, s34, v12 bitop3:0xe4
	v_bitop3_b32 v5, v71, s34, v13 bitop3:0xe4
	v_max3_f32 v50, v50, v68, v69
	v_bfe_i32 v52, v7, 18, 1
	v_bfe_i32 v53, v7, 19, 1
	s_waitcnt lgkmcnt(2)
	v_mfma_f32_32x32x16_bf16 v[34:49], v[232:235], v[146:149], v[34:49]
	v_bfe_i32 v116, v7, 24, 1
	v_bfe_i32 v118, v7, 25, 1
	v_bfe_i32 v120, v7, 26, 1
	v_bfe_i32 v121, v7, 27, 1
	v_bitop3_b32 v6, v72, s34, v14 bitop3:0xe4
	v_bitop3_b32 v7, v73, s34, v15 bitop3:0xe4
	v_max3_f32 v50, v50, v70, v5
	v_max3_f32 v50, v50, v6, v7
	v_bitop3_b32 v10, v76, s34, v52 bitop3:0xe4
	v_bitop3_b32 v11, v77, s34, v53 bitop3:0xe4
	s_waitcnt lgkmcnt(1)
	v_mfma_f32_32x32x16_bf16 v[34:49], v[236:239], v[150:153], v[34:49]
	v_max3_f32 v50, v50, v8, v9
	v_bitop3_b32 v12, v78, s34, v116 bitop3:0xe4
	v_bitop3_b32 v13, v79, s34, v118 bitop3:0xe4
	v_max3_f32 v50, v50, v10, v11
	v_bitop3_b32 v14, v80, s34, v120 bitop3:0xe4
	v_bitop3_b32 v15, v81, s34, v121 bitop3:0xe4
	v_max3_f32 v50, v50, v12, v13
	v_max3_f32 v50, v50, v14, v15
	v_mov_b32_e32 v51, v50
	s_nop 1
	v_permlane32_swap_b32_e32 v50, v51
	s_waitcnt lgkmcnt(0)
	v_mfma_f32_32x32x16_bf16 v[34:49], v[240:243], v[154:157], v[34:49]
	v_max_f32_e32 v176, v50, v51
	v_mov_b32_e32 v189, v183
	v_pk_add_f32 v[50:51], v[188:189], v[176:177]
	s_nop 0
	v_cvt_pk_bf16_f32 v52, v50, 0
	v_lshlrev_b32_e32 v52, 16, v52
	v_cmp_gt_f32_e64 s[6:7], v50, v51
	s_nop 1
	v_cndmask_b32_e64 v50, v183, v52, s[6:7]
	v_sub_f32_e32 v51, v50, v188
	v_cmp_neq_f32_e32 vcc, 0, v51
	s_cbranch_vccz .LBB0_3635
	s_branch .Lil2_cont
